# lru_final: the 1..7 leftover carry steps load all their aggregates first (one round trip) instead of one load-wait per step
# baseline (speedup 1.0000x reference)
.LBB0_1334:
	s_sub_i32 s2, s5, s3
	global_load_dwordx4 v[60:63], v[2:3], off
	s_cmp_eq_u32 s2, 1
	s_cbranch_scc1 .Llf_rem_ld_done
	v_lshl_add_u64 v[2:3], v[2:3], 0, s[6:7]
	global_load_dwordx4 v[64:67], v[2:3], off
	s_cmp_eq_u32 s2, 2
	s_cbranch_scc1 .Llf_rem_ld_done
	v_lshl_add_u64 v[2:3], v[2:3], 0, s[6:7]
	global_load_dwordx4 v[68:71], v[2:3], off
	s_cmp_eq_u32 s2, 3
	s_cbranch_scc1 .Llf_rem_ld_done
	v_lshl_add_u64 v[2:3], v[2:3], 0, s[6:7]
	global_load_dwordx4 v[72:75], v[2:3], off
	s_cmp_eq_u32 s2, 4
	s_cbranch_scc1 .Llf_rem_ld_done
	v_lshl_add_u64 v[2:3], v[2:3], 0, s[6:7]
	global_load_dwordx4 v[76:79], v[2:3], off
	s_cmp_eq_u32 s2, 5
	s_cbranch_scc1 .Llf_rem_ld_done
	v_lshl_add_u64 v[2:3], v[2:3], 0, s[6:7]
	global_load_dwordx4 v[80:83], v[2:3], off
	s_cmp_eq_u32 s2, 6
	s_cbranch_scc1 .Llf_rem_ld_done
	v_lshl_add_u64 v[2:3], v[2:3], 0, s[6:7]
	global_load_dwordx4 v[84:87], v[2:3], off
.Llf_rem_ld_done:
	s_waitcnt vmcnt(0)
	v_mul_f32_e32 v1, 0x3fb8aa3b, v60
	v_mul_f32_e32 v4, 0x3fb8aa3b, v62
	v_exp_f32_e32 v9, v1
	v_exp_f32_e32 v8, v4
	v_mov_b32_e32 v4, v63
	v_mov_b32_e32 v5, v61
	v_pk_fma_f32 v[28:29], v[28:29], v[8:9], v[4:5]
	s_cmp_eq_u32 s2, 1
	s_cbranch_scc1 .LBB0_1335
	v_mul_f32_e32 v1, 0x3fb8aa3b, v64
	v_mul_f32_e32 v4, 0x3fb8aa3b, v66
	v_exp_f32_e32 v9, v1
	v_exp_f32_e32 v8, v4
	v_mov_b32_e32 v4, v67
	v_mov_b32_e32 v5, v65
	v_pk_fma_f32 v[28:29], v[28:29], v[8:9], v[4:5]
	s_cmp_eq_u32 s2, 2
	s_cbranch_scc1 .LBB0_1335
	v_mul_f32_e32 v1, 0x3fb8aa3b, v68
	v_mul_f32_e32 v4, 0x3fb8aa3b, v70
	v_exp_f32_e32 v9, v1
	v_exp_f32_e32 v8, v4
	v_mov_b32_e32 v4, v71
	v_mov_b32_e32 v5, v69
	v_pk_fma_f32 v[28:29], v[28:29], v[8:9], v[4:5]
	s_cmp_eq_u32 s2, 3
	s_cbranch_scc1 .LBB0_1335
	v_mul_f32_e32 v1, 0x3fb8aa3b, v72
	v_mul_f32_e32 v4, 0x3fb8aa3b, v74
	v_exp_f32_e32 v9, v1
	v_exp_f32_e32 v8, v4
	v_mov_b32_e32 v4, v75
	v_mov_b32_e32 v5, v73
	v_pk_fma_f32 v[28:29], v[28:29], v[8:9], v[4:5]
	s_cmp_eq_u32 s2, 4
	s_cbranch_scc1 .LBB0_1335
	v_mul_f32_e32 v1, 0x3fb8aa3b, v76
	v_mul_f32_e32 v4, 0x3fb8aa3b, v78
	v_exp_f32_e32 v9, v1
	v_exp_f32_e32 v8, v4
	v_mov_b32_e32 v4, v79
	v_mov_b32_e32 v5, v77
	v_pk_fma_f32 v[28:29], v[28:29], v[8:9], v[4:5]
	s_cmp_eq_u32 s2, 5
	s_cbranch_scc1 .LBB0_1335
	v_mul_f32_e32 v1, 0x3fb8aa3b, v80
	v_mul_f32_e32 v4, 0x3fb8aa3b, v82
	v_exp_f32_e32 v9, v1
	v_exp_f32_e32 v8, v4
	v_mov_b32_e32 v4, v83
	v_mov_b32_e32 v5, v81
	v_pk_fma_f32 v[28:29], v[28:29], v[8:9], v[4:5]
	s_cmp_eq_u32 s2, 6
	s_cbranch_scc1 .LBB0_1335
	v_mul_f32_e32 v1, 0x3fb8aa3b, v84
	v_mul_f32_e32 v4, 0x3fb8aa3b, v86
	v_exp_f32_e32 v9, v1
	v_exp_f32_e32 v8, v4
	v_mov_b32_e32 v4, v87
	v_mov_b32_e32 v5, v85
	v_pk_fma_f32 v[28:29], v[28:29], v[8:9], v[4:5]
